# v65 + MLA loop: K-fragment LDS addresses of a step formed once in v250-253 and shared by both read groups (8 fewer VALU adds per tile)
# speedup vs baseline: 1.0603x; 1.0018x over previous
; #define LAS __attribute__((address_space(3)))
; DI void expsum(f32x16& p, float& l_reg, bf16x8& pa0, bf16x8& pa1) {
; #pragma unroll
;     for (int r = 0; r < 16; ++r) p[r] = __builtin_amdgcn_exp2f(p[r]);
;     float ps = 0.f;
; #pragma unroll
;     for (int r = 0; r < 16; ++r) ps += p[r];
;     l_reg += ps; asm volatile("" : "+v"(l_reg));
;     ...
;     ATT_PK4(p, 0, pa0); ATT_PK4(p, 8, pa1);
;     ...
; }
; DI int v_rd_base(int lane) { return ((lane & 3) << 3) | (((lane >> 2) & 3) << 6) | (((lane >> 4) & 1) << 5) | (((lane >> 5) & 1) << 8); }
; template <int OFF> DI s16x4 tr_read(int vb) { s16x4 r; asm volatile("ds_read_b64_tr_b16 %0, %1 offset:%2" : "=&v"(r) : "v"(vb), "i"(OFF) : "memory"); return r; }
; template <int H> DI void v_reads(s16x4* vf, int vb) {
;     vf[0] = tr_read<v_rd_off(0, 2 * H, 0)>(vb); vf[1] = tr_read<v_rd_off(0, 2 * H, 1)>(vb); vf[2] = tr_read<v_rd_off(0, 2 * H + 1, 0)>(vb); vf[3] = tr_read<v_rd_off(0, 2 * H + 1, 1)>(vb);
;     vf[4] = tr_read<v_rd_off(1, 2 * H, 0)>(vb); vf[5] = tr_read<v_rd_off(1, 2 * H, 1)>(vb); vf[6] = tr_read<v_rd_off(1, 2 * H + 1, 0)>(vb); vf[7] = tr_read<v_rd_off(1, 2 * H + 1, 1)>(vb);
;     vf[8] = tr_read<v_rd_off(2, 2 * H, 0)>(vb); vf[9] = tr_read<v_rd_off(2, 2 * H, 1)>(vb); vf[10] = tr_read<v_rd_off(2, 2 * H + 1, 0)>(vb); vf[11] = tr_read<v_rd_off(2, 2 * H + 1, 1)>(vb);
;     vf[12] = tr_read<v_rd_off(3, 2 * H, 0)>(vb); vf[13] = tr_read<v_rd_off(3, 2 * H, 1)>(vb); vf[14] = tr_read<v_rd_off(3, 2 * H + 1, 0)>(vb); vf[15] = tr_read<v_rd_off(3, 2 * H + 1, 1)>(vb);
; }
; DI void pv_mma(f32x16* o, const s16x4* vf, bf16x8 pa0, bf16x8 pa1) {
;     ...
; #pragma unroll
;     for (int d0 = 0; d0 < 4; ++d0) {
;         o[d0] = __builtin_amdgcn_mfma_f32_32x32x16_bf16(pa0, ATT_PK(vf[4 * d0], vf[4 * d0 + 1]), o[d0], 0, 0, 0);
;         o[d0] = __builtin_amdgcn_mfma_f32_32x32x16_bf16(pa1, ATT_PK(vf[4 * d0 + 2], vf[4 * d0 + 3]), o[d0], 0, 0, 0); }
;     ...
; }
; template <int DQK, int D0A, int D0B> DI void k_reads(bf16x8* kf, const LAS unsigned char* Ks, int half, int r32, int hi) {
; #pragma unroll
;     for (int d0 = D0A; d0 < D0B; ++d0) kf[d0 - D0A] = *(const LAS bf16x8*)(Ks + half * (32 * DQK * 2) + kswz<DQK>(r32, (d0 * 16 + hi * 8) * 2));
; }
; template <int D0A, int D0B> DI void qk_mma(f32x16& p, const bf16x8* kf, const bf16x8* qr) {
; #pragma unroll
;     for (int d0 = D0A; d0 < D0B; ++d0) {
.Lstg_mla_top_2:
	s_setprio 0
	s_mov_b32 m0, s1
	s_mov_b32 s0, s5
	s_mov_b32 s5, s44
	s_mov_b32 s44, s4
	s_lshl_b32 s4, s4, 14
	global_load_lds_dwordx4 v136, s[34:35]
	s_add_i32 m0, s1, 0x2000
	s_add_i32 s4, s52, s4
	global_load_lds_dwordx4 v138, s[34:35]
	s_add_i32 m0, s1, 0x4000
	s_add_i32 s6, s4, 0x400
	global_load_lds_dwordx4 v140, s[34:35]
	s_mov_b32 m0, s4
	s_add_i32 s1, s43, -3
	global_load_lds_dwordx4 v144, s[34:35]
	s_mov_b32 m0, s6
	s_nop 0
	global_load_lds_dwordx4 v142, s[34:35]
	s_and_b32 s1, s1, 3
	s_mulk_i32 s1, 0x6000
	v_add_u32_e32 v246, s1, v158
	v_add_u32_e32 v250, v246, v151
	v_add_u32_e32 v251, v246, v149
	v_add_u32_e32 v252, v246, v148
	v_add_u32_e32 v253, v246, v147
	s_lshl_b32 s1, s0, 14
	ds_read_b128 v[190:193], v250 offset:12416
	ds_read_b128 v[194:197], v251 offset:12416
	ds_read_b128 v[174:177], v250 offset:12288
	ds_read_b128 v[178:181], v251 offset:12288
	ds_read_b128 v[182:185], v252 offset:12288
	ds_read_b128 v[186:189], v253 offset:12288
	v_add_u32_e32 v254, s1, v130
	ds_read_b64_tr_b16 v[198:199], v254 offset:0
	ds_read_b64_tr_b16 v[200:201], v254 offset:0x800
	ds_read_b64_tr_b16 v[202:203], v254 offset:0x1000
	ds_read_b64_tr_b16 v[204:205], v254 offset:0x1800
	ds_read_b64_tr_b16 v[206:207], v254 offset:0x200
	ds_read_b64_tr_b16 v[208:209], v254 offset:0xa00
	ds_read_b64_tr_b16 v[210:211], v254 offset:0x1200
	ds_read_b64_tr_b16 v[212:213], v254 offset:0x1a00
	ds_read_b64_tr_b16 v[214:215], v254 offset:0x400
	ds_read_b64_tr_b16 v[216:217], v254 offset:0xc00
	ds_read_b64_tr_b16 v[218:219], v254 offset:0x1400
	ds_read_b64_tr_b16 v[220:221], v254 offset:0x1c00
	ds_read_b64_tr_b16 v[222:223], v254 offset:0x600
	ds_read_b64_tr_b16 v[224:225], v254 offset:0xe00
	ds_read_b64_tr_b16 v[226:227], v254 offset:0x1600
	ds_read_b64_tr_b16 v[228:229], v254 offset:0x1e00
	s_setprio 2
	v_exp_f32_e32 v64, v64
	v_exp_f32_e32 v65, v65
	v_exp_f32_e32 v66, v66
	v_exp_f32_e32 v67, v67
	v_exp_f32_e32 v68, v68
	v_exp_f32_e32 v69, v69
	v_add_f32_e32 v230, v65, v64
	v_exp_f32_e32 v70, v70
	v_add_f32_e32 v230, v66, v230
	v_exp_f32_e32 v71, v71
	v_add_f32_e32 v230, v67, v230
	v_exp_f32_e32 v72, v72
	v_add_f32_e32 v230, v68, v230
	v_exp_f32_e32 v73, v73
	v_add_f32_e32 v230, v69, v230
	v_exp_f32_e32 v74, v74
	v_add_f32_e32 v230, v70, v230
	v_exp_f32_e32 v75, v75
	v_add_f32_e32 v230, v71, v230
	v_exp_f32_e32 v76, v76
	v_add_f32_e32 v230, v72, v230
	v_exp_f32_e32 v77, v77
	v_add_f32_e32 v230, v73, v230
	v_exp_f32_e32 v78, v78
	v_add_f32_e32 v230, v74, v230
	v_exp_f32_e32 v79, v79
	v_add_f32_e32 v230, v75, v230
	v_add_f32_e32 v230, v76, v230
	v_add_f32_e32 v230, v77, v230
	v_add_f32_e32 v230, v78, v230
	v_add_f32_e32 v230, v79, v230
	v_add_f32_e32 v173, v173, v230
	v_cvt_pk_bf16_f32 v64, v64, v65
	v_cvt_pk_bf16_f32 v65, v66, v67
	v_cvt_pk_bf16_f32 v66, v68, v69
	v_cvt_pk_bf16_f32 v67, v70, v71
	v_cvt_pk_bf16_f32 v68, v72, v73
	v_cvt_pk_bf16_f32 v69, v74, v75
	v_cvt_pk_bf16_f32 v70, v76, v77
	v_cvt_pk_bf16_f32 v71, v78, v79
	s_nop 0
	v_permlane32_swap_b32_e32 v64, v66
	v_permlane32_swap_b32_e32 v65, v67
	v_permlane32_swap_b32_e32 v68, v70
	v_permlane32_swap_b32_e32 v69, v71
	s_waitcnt lgkmcnt(0)
	ds_read_b128 v[230:233], v252 offset:12416
	ds_read_b128 v[234:237], v253 offset:12416
	ds_read_b128 v[238:241], v250 offset:12544
	ds_read_b128 v[242:245], v251 offset:12544
	ds_read_b128 v[246:249], v252 offset:12544
	ds_read_b128 v[250:253], v253 offset:12544
	s_setprio 1
	v_mfma_f32_32x32x16_bf16 v[48:63], v[64:67], v[198:201], v[48:63]
	v_mfma_f32_32x32x16_bf16 v[32:47], v[64:67], v[206:209], v[32:47]
	v_mfma_f32_32x32x16_bf16 v[16:31], v[64:67], v[214:217], v[16:31]
	v_mfma_f32_32x32x16_bf16 v[0:15], v[64:67], v[222:225], v[0:15]
	v_mfma_f32_32x32x16_bf16 v[48:63], v[68:71], v[202:205], v[48:63]
	v_mfma_f32_32x32x16_bf16 v[32:47], v[68:71], v[210:213], v[32:47]
	v_mfma_f32_32x32x16_bf16 v[16:31], v[68:71], v[218:221], v[16:31]
	v_mfma_f32_32x32x16_bf16 v[0:15], v[68:71], v[226:229], v[0:15]
	s_waitcnt lgkmcnt(0)
; #define LAS __attribute__((address_space(3)))
; DI void expsum(f32x16& p, float& l_reg, bf16x8& pa0, bf16x8& pa1) {
; #pragma unroll
;     for (int r = 0; r < 16; ++r) p[r] = __builtin_amdgcn_exp2f(p[r]);
;     float ps = 0.f;
; #pragma unroll
;     for (int r = 0; r < 16; ++r) ps += p[r];
;     l_reg += ps; asm volatile("" : "+v"(l_reg));
;     ...
;     ATT_PK4(p, 0, pa0); ATT_PK4(p, 8, pa1);
;     ...
; }
; DI int v_rd_base(int lane) { return ((lane & 3) << 3) | (((lane >> 2) & 3) << 6) | (((lane >> 4) & 1) << 5) | (((lane >> 5) & 1) << 8); }
; template <int OFF> DI s16x4 tr_read(int vb) { s16x4 r; asm volatile("ds_read_b64_tr_b16 %0, %1 offset:%2" : "=&v"(r) : "v"(vb), "i"(OFF) : "memory"); return r; }
; template <int H> DI void v_reads(s16x4* vf, int vb) {
;     vf[0] = tr_read<v_rd_off(0, 2 * H, 0)>(vb); vf[1] = tr_read<v_rd_off(0, 2 * H, 1)>(vb); vf[2] = tr_read<v_rd_off(0, 2 * H + 1, 0)>(vb); vf[3] = tr_read<v_rd_off(0, 2 * H + 1, 1)>(vb);
;     vf[4] = tr_read<v_rd_off(1, 2 * H, 0)>(vb); vf[5] = tr_read<v_rd_off(1, 2 * H, 1)>(vb); vf[6] = tr_read<v_rd_off(1, 2 * H + 1, 0)>(vb); vf[7] = tr_read<v_rd_off(1, 2 * H + 1, 1)>(vb);
;     vf[8] = tr_read<v_rd_off(2, 2 * H, 0)>(vb); vf[9] = tr_read<v_rd_off(2, 2 * H, 1)>(vb); vf[10] = tr_read<v_rd_off(2, 2 * H + 1, 0)>(vb); vf[11] = tr_read<v_rd_off(2, 2 * H + 1, 1)>(vb);
;     vf[12] = tr_read<v_rd_off(3, 2 * H, 0)>(vb); vf[13] = tr_read<v_rd_off(3, 2 * H, 1)>(vb); vf[14] = tr_read<v_rd_off(3, 2 * H + 1, 0)>(vb); vf[15] = tr_read<v_rd_off(3, 2 * H + 1, 1)>(vb);
; }
; DI void pv_mma(f32x16* o, const s16x4* vf, bf16x8 pa0, bf16x8 pa1) {
;     ...
; #pragma unroll
;     for (int d0 = 0; d0 < 4; ++d0) {
;         o[d0] = __builtin_amdgcn_mfma_f32_32x32x16_bf16(pa0, ATT_PK(vf[4 * d0], vf[4 * d0 + 1]), o[d0], 0, 0, 0);
;         o[d0] = __builtin_amdgcn_mfma_f32_32x32x16_bf16(pa1, ATT_PK(vf[4 * d0 + 2], vf[4 * d0 + 3]), o[d0], 0, 0, 0); }
;     ...
; }
; template <int DQK, int D0A, int D0B> DI void k_reads(bf16x8* kf, const LAS unsigned char* Ks, int half, int r32, int hi) {
; #pragma unroll
;     for (int d0 = D0A; d0 < D0B; ++d0) kf[d0 - D0A] = *(const LAS bf16x8*)(Ks + half * (32 * DQK * 2) + kswz<DQK>(r32, (d0 * 16 + hi * 8) * 2));
; }
; template <int D0A, int D0B> DI void qk_mma(f32x16& p, const bf16x8* kf, const bf16x8* qr) {
; #pragma unroll
;     for (int d0 = D0A; d0 < D0B; ++d0) {
	v_mfma_f32_32x32x16_bf16 v[64:79], v[174:177], v[80:83], 0
	v_mfma_f32_32x32x16_bf16 v[64:79], v[178:181], v[84:87], v[64:79]
	v_mfma_f32_32x32x16_bf16 v[64:79], v[182:185], v[88:91], v[64:79]
	v_mfma_f32_32x32x16_bf16 v[64:79], v[186:189], v[92:95], v[64:79]
	v_mfma_f32_32x32x16_bf16 v[64:79], v[190:193], v[96:99], v[64:79]
	v_mfma_f32_32x32x16_bf16 v[64:79], v[194:197], v[100:103], v[64:79]
	v_mfma_f32_32x32x16_bf16 v[64:79], v[230:233], v[104:107], v[64:79]
	v_mfma_f32_32x32x16_bf16 v[64:79], v[234:237], v[108:111], v[64:79]
	v_mfma_f32_32x32x16_bf16 v[64:79], v[238:241], v[112:115], v[64:79]
	v_mfma_f32_32x32x16_bf16 v[64:79], v[242:245], v[116:119], v[64:79]
	v_mfma_f32_32x32x16_bf16 v[64:79], v[246:249], v[120:123], v[64:79]
	v_mfma_f32_32x32x16_bf16 v[64:79], v[250:253], v[124:127], v[64:79]
	s_setprio 0
	s_add_i32 s4, s43, -2
	s_and_b32 s4, s4, 3
	s_mulk_i32 s4, 0x6000
	v_add_u32_e32 v246, s4, v158
	v_add_u32_e32 v250, v246, v151
	v_add_u32_e32 v251, v246, v149
	v_add_u32_e32 v252, v246, v148
	v_add_u32_e32 v253, v246, v147
	ds_read_b128 v[190:193], v250 offset:128
	ds_read_b128 v[194:197], v251 offset:128
	ds_read_b128 v[174:177], v250
	ds_read_b128 v[178:181], v251
	ds_read_b128 v[182:185], v252
	ds_read_b128 v[186:189], v253
	ds_read_b64_tr_b16 v[198:199], v254 offset:0x2000
	ds_read_b64_tr_b16 v[200:201], v254 offset:0x2800
	ds_read_b64_tr_b16 v[202:203], v254 offset:0x3000
	ds_read_b64_tr_b16 v[204:205], v254 offset:0x3800
	ds_read_b64_tr_b16 v[206:207], v254 offset:0x2200
	ds_read_b64_tr_b16 v[208:209], v254 offset:0x2a00
	ds_read_b64_tr_b16 v[210:211], v254 offset:0x3200
	ds_read_b64_tr_b16 v[212:213], v254 offset:0x3a00
	ds_read_b64_tr_b16 v[214:215], v254 offset:0x2400
	ds_read_b64_tr_b16 v[216:217], v254 offset:0x2c00
	ds_read_b64_tr_b16 v[218:219], v254 offset:0x3400
	ds_read_b64_tr_b16 v[220:221], v254 offset:0x3c00
	ds_read_b64_tr_b16 v[222:223], v254 offset:0x2600
	ds_read_b64_tr_b16 v[224:225], v254 offset:0x2e00
	ds_read_b64_tr_b16 v[226:227], v254 offset:0x3600
	ds_read_b64_tr_b16 v[228:229], v254 offset:0x3e00
	s_setprio 2
	v_exp_f32_e32 v64, v64
	v_exp_f32_e32 v65, v65
	v_exp_f32_e32 v66, v66
	v_exp_f32_e32 v67, v67
	v_exp_f32_e32 v68, v68
	v_exp_f32_e32 v69, v69
	v_add_f32_e32 v230, v65, v64
	v_exp_f32_e32 v70, v70
	v_add_f32_e32 v230, v66, v230
	v_exp_f32_e32 v71, v71
	v_add_f32_e32 v230, v67, v230
	v_exp_f32_e32 v72, v72
	v_add_f32_e32 v230, v68, v230
	v_exp_f32_e32 v73, v73
	v_add_f32_e32 v230, v69, v230
	v_exp_f32_e32 v74, v74
	v_add_f32_e32 v230, v70, v230
	v_exp_f32_e32 v75, v75
	v_add_f32_e32 v230, v71, v230
	v_exp_f32_e32 v76, v76
	v_add_f32_e32 v230, v72, v230
	v_exp_f32_e32 v77, v77
	v_add_f32_e32 v230, v73, v230
	v_exp_f32_e32 v78, v78
	v_add_f32_e32 v230, v74, v230
	v_exp_f32_e32 v79, v79
	v_add_f32_e32 v230, v75, v230
	v_add_f32_e32 v230, v76, v230
	v_add_f32_e32 v230, v77, v230
	v_add_f32_e32 v230, v78, v230
	v_add_f32_e32 v230, v79, v230
	v_add_f32_e32 v173, v173, v230
	v_cvt_pk_bf16_f32 v64, v64, v65
	v_cvt_pk_bf16_f32 v65, v66, v67
	v_cvt_pk_bf16_f32 v66, v68, v69
	v_cvt_pk_bf16_f32 v67, v70, v71
	v_cvt_pk_bf16_f32 v68, v72, v73
	v_cvt_pk_bf16_f32 v69, v74, v75
	v_cvt_pk_bf16_f32 v70, v76, v77
	v_cvt_pk_bf16_f32 v71, v78, v79
	s_nop 0
	v_permlane32_swap_b32_e32 v64, v66
	v_permlane32_swap_b32_e32 v65, v67
	v_permlane32_swap_b32_e32 v68, v70
	v_permlane32_swap_b32_e32 v69, v71
	s_waitcnt lgkmcnt(0)
	ds_read_b128 v[230:233], v252 offset:128
	ds_read_b128 v[234:237], v253 offset:128
	ds_read_b128 v[238:241], v250 offset:256
	ds_read_b128 v[242:245], v251 offset:256
	ds_read_b128 v[246:249], v252 offset:256
	ds_read_b128 v[250:253], v253 offset:256
	s_setprio 1
	s_cmp_lt_u32 s33, 0x100
	s_cbranch_scc1 .Lstg_mla_mid_3
	s_waitcnt vmcnt(5)
	s_barrier
